# v59 + MLA half 1 head: first QK MFMA leads behind the DMA block, the 8 v_fma + 6 v_exp run in its shadow
# baseline (speedup 1.0000x reference)
.LBB0_543:
	s_mov_b32 s23, s17
	s_mov_b32 s17, s0
	s_add_i32 s71, 0, 0x10000
	ds_read_b128 v[66:69], v174 offset:49152
	ds_read_b128 v[70:73], v174 offset:57344
	ds_read_b128 v[206:209], v176 offset:49152
	ds_read_b128 v[210:213], v176 offset:57344
	s_add_u32 s4, s38, s20
	s_addc_u32 s5, s39, s21
	s_add_u32 s24, s4, 0x149ec400
	s_addc_u32 s25, s5, 0
	s_mov_b32 m0, s90
	v_lshl_add_u64 v[254:255], v[246:247], 0, s[24:25]
	s_lshl_b32 s18, s22, 14
	global_load_lds_dwordx4 v[254:255], off
	s_add_u32 s24, s4, 0x14a0c400
	s_addc_u32 s25, s5, 0
	s_mov_b32 m0, s91
	v_lshl_add_u64 v[254:255], v[246:247], 0, s[24:25]
	s_add_i32 s1, s89, s18
	global_load_lds_dwordx4 v[254:255], off
	s_add_u32 s24, s4, 0x149ec500
	s_addc_u32 s25, s5, 0
	s_mov_b32 m0, s1
	v_lshl_add_u64 v[254:255], v[248:249], 0, s[24:25]
	global_load_lds_dwordx4 v[254:255], off
	s_add_u32 s24, s4, 0x14a0c500
	s_addc_u32 s25, s5, 0
	s_add_i32 m0, s1, 0x2000
	v_lshl_add_u64 v[254:255], v[248:249], 0, s[24:25]
	global_load_lds_dwordx4 v[254:255], off
	s_add_u32 s4, s38, s88
	s_addc_u32 s5, s39, s87
	s_add_u32 s4, s4, s36
	s_addc_u32 s5, s5, s37
	s_mov_b32 m0, s92
	v_lshl_add_u64 v[254:255], v[250:251], 0, s[4:5]
	global_load_lds_dwordx4 v[254:255], off
	s_waitcnt lgkmcnt(3)
	v_mfma_f32_32x32x16_bf16 v[82:97], v[66:69], v[142:145], 0
	v_fma_f32 v152, v74, s34, v146
	v_fma_f32 v153, v75, s34, v146
	v_fma_f32 v150, v76, s34, v146
	v_fma_f32 v151, v77, s34, v146
	v_fma_f32 v148, v78, s34, v146
	v_fma_f32 v149, v79, s34, v146
	v_fma_f32 v147, v81, s34, v146
	v_fma_f32 v146, v80, s34, v146
	v_exp_f32_e32 v229, v229
	v_exp_f32_e32 v231, v231
	v_exp_f32_e32 v227, v227
	v_exp_f32_e32 v230, v230
	v_exp_f32_e32 v226, v226
	v_exp_f32_e32 v228, v228
	s_add_i32 s0, 0, 0x16000
	v_exp_f32_e32 v240, v146
	v_add_f32_e32 v146, 0, v229
	v_add_f32_e32 v146, v231, v146
	v_add_f32_e32 v146, v227, v146
	v_add_f32_e32 v146, v230, v146
	v_add_f32_e32 v146, v226, v146
	v_exp_f32_e32 v224, v224
	v_exp_f32_e32 v225, v225
	v_exp_f32_e32 v221, v221
	v_exp_f32_e32 v223, v223
	s_waitcnt lgkmcnt(0)
	v_mfma_f32_32x32x16_bf16 v[66:81], v[70:73], v[142:145], 0
	v_exp_f32_e32 v220, v220
	v_exp_f32_e32 v222, v222
	v_add_f32_e32 v146, v228, v146
	v_add_f32_e32 v146, v224, v146
	v_add_f32_e32 v146, v225, v146
	v_add_f32_e32 v146, v221, v146
	v_add_f32_e32 v146, v223, v146
	v_add_f32_e32 v146, v220, v146
	v_add_f32_e32 v146, v222, v146
	v_exp_f32_e32 v217, v217
	v_exp_f32_e32 v219, v219
	v_exp_f32_e32 v216, v216
	v_exp_f32_e32 v218, v218
	v_mfma_f32_32x32x16_bf16 v[82:97], v[206:209], v[138:141], v[82:97]
	v_exp_f32_e32 v164, v164
	v_add_f32_e32 v146, v217, v146
	v_exp_f32_e32 v165, v165
	v_add_f32_e32 v146, v219, v146
	v_exp_f32_e32 v197, v162
	v_add_f32_e32 v146, v216, v146
	v_add_f32_e32 v146, v218, v146
	v_mfma_f32_32x32x16_bf16 v[66:81], v[210:213], v[138:141], v[66:81]
	ds_read_b128 v[206:209], v178 offset:49152
	ds_read_b128 v[210:213], v178 offset:57344
	v_exp_f32_e32 v156, v156
	v_add_f32_e32 v146, v164, v146
	v_exp_f32_e32 v157, v157
	v_add_f32_e32 v146, v165, v146
	v_add_f32_e32 v146, v197, v146
	v_exp_f32_e32 v241, v147
	s_waitcnt lgkmcnt(0)
	v_mfma_f32_32x32x16_bf16 v[82:97], v[206:209], v[134:137], v[82:97]
	v_mfma_f32_32x32x16_bf16 v[66:81], v[210:213], v[134:137], v[66:81]
	ds_read_b128 v[208:211], v180 offset:49152
	ds_read_b128 v[212:215], v180 offset:57344
	s_waitcnt lgkmcnt(0)
	v_mfma_f32_32x32x16_bf16 v[82:97], v[208:211], v[130:133], v[82:97]
	v_mfma_f32_32x32x16_bf16 v[66:81], v[212:215], v[130:133], v[66:81]
	ds_read_b128 v[208:211], v182 offset:49152
	ds_read_b128 v[212:215], v182 offset:57344
	s_waitcnt lgkmcnt(0)
	v_mfma_f32_32x32x16_bf16 v[82:97], v[208:211], v[126:129], v[82:97]
	v_mfma_f32_32x32x16_bf16 v[66:81], v[212:215], v[126:129], v[66:81]
	ds_read_b128 v[210:213], v186 offset:49152
	ds_read_b128 v[232:235], v186 offset:57344
	s_waitcnt lgkmcnt(0)
	v_mfma_f32_32x32x16_bf16 v[82:97], v[210:213], v[122:125], v[82:97]
	v_mfma_f32_32x32x16_bf16 v[66:81], v[232:235], v[122:125], v[66:81]
	ds_read_b128 v[210:213], v188 offset:49152
	ds_read_b128 v[232:235], v188 offset:57344
	s_waitcnt lgkmcnt(0)
	v_mfma_f32_32x32x16_bf16 v[82:97], v[210:213], v[118:121], v[82:97]
	v_mfma_f32_32x32x16_bf16 v[66:81], v[232:235], v[118:121], v[66:81]
	ds_read_b128 v[212:215], v190 offset:49152
	ds_read_b128 v[232:235], v190 offset:57344
	s_waitcnt lgkmcnt(0)
	v_mfma_f32_32x32x16_bf16 v[82:97], v[212:215], v[114:117], v[82:97]
	v_mfma_f32_32x32x16_bf16 v[66:81], v[232:235], v[114:117], v[66:81]
	ds_read_b128 v[212:215], v192 offset:8192
	ds_read_b128 v[232:235], v192 offset:12288
	s_waitcnt lgkmcnt(0)
	v_mfma_f32_32x32x16_bf16 v[82:97], v[212:215], v[110:113], v[82:97]
	v_exp_f32_e32 v215, v163
	s_nop 0
	v_add_f32_e32 v146, v215, v146
	v_mfma_f32_32x32x16_bf16 v[66:81], v[232:235], v[110:113], v[66:81]
	s_lshl_b32 s24, s17, 14
	v_add_u32_e32 v245, s24, v200
	ds_read_b64_tr_b16 v[206:207], v245 offset:0
	ds_read_b64_tr_b16 v[208:209], v245 offset:0x800
	ds_read_b64_tr_b16 v[210:211], v245 offset:0x1000
	ds_read_b64_tr_b16 v[212:213], v245 offset:0x1800
	ds_read_b128 v[232:235], v194 offset:8192
	ds_read_b128 v[236:239], v194 offset:12288
	v_add_f32_e32 v146, v156, v146
	v_add_f32_e32 v146, v157, v146
	s_waitcnt lgkmcnt(0)
	v_mfma_f32_32x32x16_bf16 v[82:97], v[232:235], v[106:109], v[82:97]
	v_mfma_f32_32x32x16_bf16 v[66:81], v[236:239], v[106:109], v[66:81]
	ds_read_b128 v[232:235], v196 offset:8192
	ds_read_b128 v[236:239], v196 offset:12288
	s_waitcnt lgkmcnt(0)
	v_mfma_f32_32x32x16_bf16 v[82:97], v[232:235], v[102:105], v[82:97]
	v_mfma_f32_32x32x16_bf16 v[66:81], v[236:239], v[102:105], v[66:81]
	ds_read_b128 v[232:235], v199 offset:8192
	ds_read_b128 v[236:239], v199 offset:12288
	s_waitcnt lgkmcnt(0)
	v_mfma_f32_32x32x16_bf16 v[82:97], v[232:235], v[98:101], v[82:97]
	v_exp_f32_e32 v232, v154
	v_exp_f32_e32 v233, v155
	v_exp_f32_e32 v234, v152
	v_exp_f32_e32 v235, v153
	v_add_f32_e32 v146, v232, v146
	v_add_f32_e32 v146, v233, v146
	v_add_f32_e32 v146, v234, v146
	v_mfma_f32_32x32x16_bf16 v[66:81], v[236:239], v[98:101], v[66:81]
	v_exp_f32_e32 v236, v150
	v_exp_f32_e32 v237, v151
	v_exp_f32_e32 v238, v148
	v_exp_f32_e32 v239, v149
	v_add_f32_e32 v146, v235, v146
	v_add_f32_e32 v146, v236, v146
	v_add_f32_e32 v146, v237, v146
	v_add_f32_e32 v146, v238, v146
	v_add_f32_e32 v146, v239, v146
	v_add_f32_e32 v146, v240, v146
	v_add_f32_e32 v162, v241, v146
	v_mov_b32_e32 v163, v162
	s_nop 1
	v_permlane32_swap_b32_e32 v162, v163
	v_cvt_pk_bf16_f32 v146, v229, v231
	v_cvt_pk_bf16_f32 v147, v227, v230
	v_cvt_pk_bf16_f32 v148, v226, v228
	v_cvt_pk_bf16_f32 v149, v224, v225
	v_cvt_pk_bf16_f32 v150, v221, v223
	v_cvt_pk_bf16_f32 v151, v220, v222
	v_cvt_pk_bf16_f32 v152, v217, v219
	v_cvt_pk_bf16_f32 v153, v216, v218
	v_cvt_pk_bf16_f32 v154, v164, v165
	v_cvt_pk_bf16_f32 v155, v197, v215
	v_cvt_pk_bf16_f32 v156, v156, v157
	v_cvt_pk_bf16_f32 v157, v232, v233
	v_cvt_pk_bf16_f32 v216, v234, v235
	v_cvt_pk_bf16_f32 v217, v236, v237
	v_cvt_pk_bf16_f32 v218, v238, v239
	v_cvt_pk_bf16_f32 v219, v240, v241
	s_nop 0
	v_permlane32_swap_b32_e32 v146, v148
	v_permlane32_swap_b32_e32 v147, v149
	v_permlane32_swap_b32_e32 v150, v152
	v_permlane32_swap_b32_e32 v151, v153
	v_permlane32_swap_b32_e32 v154, v156
	v_permlane32_swap_b32_e32 v155, v157
	v_permlane32_swap_b32_e32 v216, v218
	v_permlane32_swap_b32_e32 v217, v219
	s_lshl_b32 s24, s17, 14
	v_add_u32_e32 v197, s24, v200
	ds_read_b64_tr_b16 v[228:229], v197 offset:0x2000
	ds_read_b64_tr_b16 v[230:231], v197 offset:0x2800
	ds_read_b64_tr_b16 v[232:233], v197 offset:0x3000
	ds_read_b64_tr_b16 v[234:235], v197 offset:0x3800
	s_nop 0
	v_mfma_f32_32x32x16_bf16 v[2:17], v[146:149], v[206:209], v[2:17]
	ds_read_b64_tr_b16 v[220:221], v197 offset:0x200
	ds_read_b64_tr_b16 v[222:223], v197 offset:0xa00
	v_max_f32_e32 v164, v83, v83
	v_max_f32_e32 v165, v82, v82
	v_max_f32_e32 v164, v165, v164
	v_max3_f32 v164, v164, v84, v85
	v_max3_f32 v164, v164, v86, v87
	v_mfma_f32_32x32x16_bf16 v[2:17], v[150:153], v[210:213], v[2:17]
	ds_read_b64_tr_b16 v[224:225], v197 offset:0x1200
	ds_read_b64_tr_b16 v[226:227], v197 offset:0x1a00
	v_max3_f32 v164, v164, v88, v89
	v_max3_f32 v164, v164, v90, v91
	v_max3_f32 v164, v164, v92, v93
	v_max3_f32 v164, v164, v94, v95
	v_max3_f32 v164, v164, v96, v97
	s_waitcnt lgkmcnt(6)
	v_mfma_f32_32x32x16_bf16 v[2:17], v[154:157], v[228:231], v[2:17]
	ds_read_b64_tr_b16 v[228:229], v197 offset:0x2200
	ds_read_b64_tr_b16 v[230:231], v197 offset:0x2a00
	ds_read_b64_tr_b16 v[236:237], v197 offset:0x3200
	ds_read_b64_tr_b16 v[238:239], v197 offset:0x3a00
	s_waitcnt lgkmcnt(8)
	v_mfma_f32_32x32x16_bf16 v[2:17], v[216:219], v[232:235], v[2:17]
	s_waitcnt lgkmcnt(6)
	v_mfma_f32_32x32x16_bf16 v[50:65], v[146:149], v[220:223], v[50:65]
	v_max3_f32 v164, v164, v66, v67
	v_max3_f32 v164, v164, v68, v69
	v_max3_f32 v164, v164, v70, v71
	v_max3_f32 v164, v164, v72, v73
	v_max3_f32 v164, v164, v74, v75
	v_max3_f32 v164, v164, v76, v77
	v_max3_f32 v164, v164, v78, v79
	s_waitcnt lgkmcnt(4)
	v_mfma_f32_32x32x16_bf16 v[50:65], v[150:153], v[224:227], v[50:65]
	v_max3_f32 v164, v164, v80, v81
	v_mov_b32_e32 v165, v164
	s_nop 1
	v_permlane32_swap_b32_e32 v164, v165
	ds_read_b64_tr_b16 v[220:221], v197 offset:0x400
	v_max_f32_e32 v165, v165, v165
	v_max_f32_e32 v164, v164, v164
	s_waitcnt lgkmcnt(3)
	v_mfma_f32_32x32x16_bf16 v[50:65], v[154:157], v[228:231], v[50:65]
	ds_read_b64_tr_b16 v[222:223], v197 offset:0xc00
	v_max_f32_e32 v164, v164, v165
	v_max_f32_e32 v165, v202, v202
	ds_read_b64_tr_b16 v[224:225], v197 offset:0x1400
	v_max_f32_e32 v165, v165, v164
	ds_read_b64_tr_b16 v[226:227], v197 offset:0x1c00
	v_sub_f32_e32 v215, v164, v202
	s_waitcnt lgkmcnt(4)
	v_mfma_f32_32x32x16_bf16 v[50:65], v[216:219], v[236:239], v[50:65]
	v_sub_f32_e32 v164, v202, v165
	ds_read_b64_tr_b16 v[228:229], v197 offset:0x2400
	v_mul_f32_e32 v164, 0x3dd53b94, v164
	ds_read_b64_tr_b16 v[230:231], v197 offset:0x2c00
	v_exp_f32_e32 v164, v164
	ds_read_b64_tr_b16 v[232:233], v197 offset:0x3400
	v_cmp_ge_f32_e32 vcc, s77, v215
	ds_read_b64_tr_b16 v[234:235], v197 offset:0x3c00
	s_cmp_eq_u64 vcc, exec
	s_cselect_b64 s[4:5], -1, 0
	v_cndmask_b32_e64 v164, v164, 1.0, s[4:5]
	s_waitcnt lgkmcnt(6)
	v_mfma_f32_32x32x16_bf16 v[34:49], v[146:149], v[220:223], v[34:49]
	ds_read_b64_tr_b16 v[220:221], v197 offset:0x600
	ds_read_b64_tr_b16 v[222:223], v197 offset:0xe00
	s_waitcnt lgkmcnt(6)
	v_mfma_f32_32x32x16_bf16 v[34:49], v[150:153], v[224:227], v[34:49]
	ds_read_b64_tr_b16 v[224:225], v197 offset:0x1600
	ds_read_b64_tr_b16 v[226:227], v197 offset:0x1e00
	s_waitcnt lgkmcnt(6)
	v_mfma_f32_32x32x16_bf16 v[34:49], v[154:157], v[228:231], v[34:49]
	ds_read_b64_tr_b16 v[228:229], v197 offset:0x2600
	ds_read_b64_tr_b16 v[230:231], v197 offset:0x2e00
	ds_read_b64_tr_b16 v[236:237], v197 offset:0x3600
	ds_read_b64_tr_b16 v[238:239], v197 offset:0x3e00
	s_waitcnt lgkmcnt(8)
	v_mfma_f32_32x32x16_bf16 v[34:49], v[216:219], v[232:235], v[34:49]
	s_waitcnt lgkmcnt(6)
	v_mfma_f32_32x32x16_bf16 v[18:33], v[146:149], v[220:223], v[18:33]
	v_cmp_gt_f32_e32 vcc, 1.0, v164
	s_waitcnt lgkmcnt(4)
	v_mfma_f32_32x32x16_bf16 v[18:33], v[150:153], v[224:227], v[18:33]
	s_waitcnt lgkmcnt(2)
	v_mfma_f32_32x32x16_bf16 v[18:33], v[154:157], v[228:231], v[18:33]
	s_waitcnt lgkmcnt(0)
	v_mfma_f32_32x32x16_bf16 v[18:33], v[216:219], v[236:239], v[18:33]
	s_cbranch_vccz .LBB0_547
	s_and_saveexec_b64 s[0:1], s[2:3]
	ds_write_b32 v170, v164 offset:128
	s_or_b64 exec, exec, s[0:1]
	s_waitcnt lgkmcnt(0)
	ds_read_b128 v[146:149], v158 offset:224
	ds_read_b128 v[150:153], v158 offset:192
	ds_read_b128 v[154:157], v158 offset:160
	ds_read_b128 v[216:219], v158 offset:128
	s_waitcnt lgkmcnt(0)
	v_pk_mul_f32 v[16:17], v[16:17], v[148:149]
	v_pk_mul_f32 v[12:13], v[12:13], v[152:153]
	v_pk_mul_f32 v[8:9], v[8:9], v[156:157]
	v_pk_mul_f32 v[4:5], v[4:5], v[218:219]
	v_pk_mul_f32 v[14:15], v[14:15], v[146:147]
	v_pk_mul_f32 v[10:11], v[10:11], v[150:151]
	v_pk_mul_f32 v[6:7], v[6:7], v[154:155]
	v_pk_mul_f32 v[2:3], v[2:3], v[216:217]
	v_pk_mul_f32 v[64:65], v[64:65], v[148:149]
	v_pk_mul_f32 v[60:61], v[60:61], v[152:153]
	v_pk_mul_f32 v[56:57], v[56:57], v[156:157]
	v_pk_mul_f32 v[52:53], v[52:53], v[218:219]
	v_pk_mul_f32 v[62:63], v[62:63], v[146:147]
	v_pk_mul_f32 v[58:59], v[58:59], v[150:151]
	v_pk_mul_f32 v[54:55], v[54:55], v[154:155]
	v_pk_mul_f32 v[50:51], v[50:51], v[216:217]
	v_pk_mul_f32 v[48:49], v[48:49], v[148:149]
	v_pk_mul_f32 v[44:45], v[44:45], v[152:153]
	v_pk_mul_f32 v[40:41], v[40:41], v[156:157]
	v_pk_mul_f32 v[36:37], v[36:37], v[218:219]
	v_pk_mul_f32 v[46:47], v[46:47], v[146:147]
	v_pk_mul_f32 v[42:43], v[42:43], v[150:151]
	v_pk_mul_f32 v[38:39], v[38:39], v[154:155]
	v_pk_mul_f32 v[34:35], v[34:35], v[216:217]
	v_pk_mul_f32 v[32:33], v[32:33], v[148:149]
	v_pk_mul_f32 v[28:29], v[28:29], v[152:153]
	v_pk_mul_f32 v[24:25], v[24:25], v[156:157]
	v_pk_mul_f32 v[20:21], v[20:21], v[218:219]
	v_pk_mul_f32 v[30:31], v[30:31], v[146:147]
	v_pk_mul_f32 v[26:27], v[26:27], v[150:151]
	v_pk_mul_f32 v[22:23], v[22:23], v[154:155]
	v_pk_mul_f32 v[18:19], v[18:19], v[216:217]
